# compressed-branch loop hand-scheduled too; static s_setprio 1 for waves 4-7 during the attention phase
# baseline (speedup 1.0000x reference)
; #define LAS __attribute__((address_space(3)))
; __device__ __forceinline__ void attn_unit(unsigned char* ws, LAS unsigned char* lds, int b, int g, int c, const int tid) {
;     const int lane = tid & 63, w = tid >> 6, col = lane & 31, h = lane >> 5, r = col >> 3, qi = col & 7;
;     const int q = 8 * w + qi, t = 64 * c + q, head = g * 4 + r;
;     const size_t row = (size_t)b * SEQ + t;
;     const float slope2 = exp2f(-(float)(head + 1)) * LOG2E;
;     const bf16_t* Qp = (const bf16_t*)(ws + WS_Q) + row * 512 + head * 64 + 8 * h;
; __device__ __forceinline__ void attn_phase(unsigned char* ws, LAS unsigned char* lds, const int tid, const int bid, const int l) {
;     unsigned* ctr = (unsigned*)(ws + WS_CTL) + 3584 + 64 * l;
;     volatile LAS int* slot = (volatile LAS int*)(lds + LDS_MISC + 48);
;     if (tid == 0) slot[0] = (int)__hip_atomic_fetch_add(ctr, 1u, __ATOMIC_RELAXED, __HIP_MEMORY_SCOPE_AGENT);
;     __syncthreads();
;     int u = slot[0];
;     while (u < 1024) {
;         __syncthreads();
;         if (tid == 0) slot[0] = (int)__hip_atomic_fetch_add(ctr, 1u, __ATOMIC_RELAXED, __HIP_MEMORY_SCOPE_AGENT);
;         int b, g, c;
;         if (u < 384) { g = 1; c = 63 - (u >> 3); b = u & 7; }
;         else if (u < 768) { const int v = u - 384; g = 0; c = 63 - (v >> 3); b = v & 7; }
;         else { const int v = u - 768; c = 15 - (v >> 4); g = (v >> 3) & 1; b = v & 7; }
;         attn_unit(ws, lds, b, g, c, tid);
;         __syncthreads();
;         u = slot[0];
.LBB0_129:
	s_or_b64 exec, exec, s[4:5]
	v_readlane_b32 s4, v255, 8
	s_waitcnt lgkmcnt(0)
	s_barrier
	v_mov_b32_e32 v1, s4
	ds_read_b32 v1, v1
	s_movk_i32 s4, 0x3ff
	s_waitcnt lgkmcnt(0)
	v_cmp_lt_i32_e32 vcc, s4, v1
	v_readfirstlane_b32 s14, v1
	s_cbranch_vccnz .LBB0_287
	v_readfirstlane_b32 s4, v178
	s_nop 3
	s_lshr_b32 s4, s4, 8
	s_cmp_eq_u32 s4, 0
	s_cbranch_scc1 .Lattn_prio_done
	s_setprio 1
.Lattn_prio_done:
	s_add_u32 s37, s86, 0x1a200000
	s_addc_u32 s40, s87, 0
	s_add_u32 s41, s86, 0x1a280000
	s_addc_u32 s42, s87, 0
	s_add_u32 s92, s86, 0x19a00000
	s_addc_u32 s93, s87, 0
	s_add_u32 s43, s86, 0x11200000
	s_addc_u32 s44, s87, 0
	s_add_u32 s45, s86, 0x10a00000
	s_addc_u32 s46, s87, 0
	s_add_u32 s47, s86, 0x12200000
	v_ashrrev_i32_e32 v2, 3, v178
	s_addc_u32 s48, s87, 0
	v_bfe_u32 v1, v178, 5, 1
	v_bfi_b32 v198, -8, v2, v178
	s_movk_i32 s4, 0x2080
	v_lshlrev_b32_e32 v5, 3, v178
	s_add_u32 s49, s86, 0x11a00000
	v_and_b32_e32 v197, -8, v2
	v_lshlrev_b32_e32 v2, 3, v1
	v_cmp_gt_i32_e64 s[8:9], s4, v178
	v_lshlrev_b32_e32 v3, 2, v178
	v_readlane_b32 s4, v255, 9
	v_lshlrev_b32_e32 v6, 3, v198
	s_addc_u32 s82, s87, 0
	v_lshlrev_b32_e32 v4, 2, v1
	v_add_u32_e32 v1, 0, v5
	v_and_b32_e32 v179, 63, v178
	v_add_u32_e32 v199, s4, v3
	s_add_u32 s94, s86, 0x15a00000
	v_readlane_b32 s4, v255, 10
	v_add_u32_e32 v208, 0x12a00, v1
	v_add_u32_e32 v1, 0, v6
	v_bfe_u32 v196, v178, 3, 2
	v_cmp_gt_u32_e64 s[10:11], 64, v178
	v_xor_b32_e32 v200, 4, v3
	v_xor_b32_e32 v201, 8, v3
	v_xor_b32_e32 v202, 16, v3
	v_xor_b32_e32 v203, 32, v3
	v_xor_b32_e32 v204, 64, v3
	v_xor_b32_e32 v205, 0x80, v3
	v_cmp_eq_u32_e64 s[12:13], 0, v179
	s_addc_u32 s95, s87, 0
	v_add_u32_e32 v206, s4, v3
	v_add_u32_e32 v207, 0xfffffe00, v178
	v_lshlrev_b32_e32 v180, 1, v2
	v_add_u32_e32 v209, 0x12a00, v1
	v_lshlrev_b32_e32 v182, 1, v4
	v_mov_b32_e32 v181, v0
	s_branch .LBB0_132

; #define LAS __attribute__((address_space(3)))
; template <int MODE  > ...
;     ...
;     unsigned long long rem = blockmask;
;     if (!rem) return;
;     int j = 63 - __builtin_clzll(rem); rem &= ~(1ull << j);
;     u32x4 kreg, vreg;
;     kreg = *(const u32x4*)(Kg + (size_t)(64 * j + skey) * 128 + schunk * 8);
;     if (NEEDV) vreg = *(const u32x4*)(Vg + (size_t)(64 * j + skey) * 128 + schunk * 8);
;     int cur = 0;
;     {
;         LAS bf16_t* kb = (LAS bf16_t*)(lds + A_KBUF) + cur * 64 * KPITCH;
;         *(LAS u32x4*)(kb + skey * KPITCH + schunk * 8) = kreg;
;         if (NEEDV) { LAS bf16_t* vb = (LAS bf16_t*)(lds + A_VBUF) + cur * 64 * VPITCH;
;             *(LAS u32x4*)(vb + skey * VPITCH + schunk * 8) = vreg; }
;     }
;     __syncthreads();
;     for (;;) {
;         const bool has_next = rem != 0ull; int jn = 0;
;         if (has_next) { jn = 63 - __builtin_clzll(rem); rem &= ~(1ull << jn);
;             kreg = *(const u32x4*)(Kg + (size_t)(64 * jn + skey) * 128 + schunk * 8);
;             if (NEEDV) vreg = *(const u32x4*)(Vg + (size_t)(64 * jn + skey) * 128 + schunk * 8); }
; __device__ __forceinline__ void attn_unit(unsigned char* ws, LAS unsigned char* lds, int b, int g, int c, const int tid) {
;     ...
;     const size_t boff = (size_t)b * SEQ * 128 + g * 64;
;     const int nvalid = 4 * c + 3 > 255 ? 255 : 4 * c + 3;
;     const int nkb = (nvalid + 63) >> 6;
;     const unsigned long long cmpmask = (nkb >= 64) ? ~0ull : ((1ull << nkb) - 1ull);
;     const bf16_t* KCp = (const bf16_t*)(ws + WS_KC) + (size_t)b * 256 * 128 + g * 64;
;     const bf16_t* VCp = (const bf16_t*)(ws + WS_VC) + (size_t)b * 256 * 128 + g * 64;
;     AttnState st; st.m = -1e29f; st.l = 0.f; st.o0 = (f32x16){}; st.o1 = (f32x16){};
;     attn_pass<0>(lds, KCp, VCp, cmpmask, qf, st, t, slope2, 0ull, w, lane, tid, c);
.LBB0_145:
	s_or_b64 exec, exec, s[4:5]
	s_lshl_b32 s69, s83, 2
	s_add_i32 s4, s69, 0x42
	s_lshl_b32 s62, s16, 6
	s_lshr_b32 s4, s4, 6
	s_cmp_lt_u32 s83, 64
	s_cselect_b32 s4, s4, 4
	s_lshl_b64 s[4:5], -1, s4
	s_not_b64 s[20:21], s[4:5]
	s_lshl_b32 s14, s68, 16
	s_add_u32 s15, s37, s14
	s_addc_u32 s17, s40, 0
	s_lshl_b32 s16, s16, 7
	s_add_u32 s18, s15, s16
	s_addc_u32 s19, s17, 0
	s_add_u32 s14, s41, s14
	s_addc_u32 s15, s42, 0
	s_add_u32 s14, s14, s16
	s_flbit_i32_b64 s16, s[20:21]
	s_addc_u32 s15, s15, 0
	v_mov_b32_e32 v1, v178
	v_mov_b32_e32 v18, v179
	s_xor_b32 s84, s16, 63
	s_lshl_b32 s85, s84, 6
	v_ashrrev_i32_e32 v211, 3, v1
	v_add_u32_e32 v2, s85, v211
	v_ashrrev_i32_e32 v3, 31, v2
	v_lshlrev_b64 v[2:3], 8, v[2:3]
	v_lshlrev_b32_e32 v1, 4, v1
	v_lshl_add_u64 v[4:5], s[18:19], 0, v[2:3]
	v_and_b32_e32 v16, 0x70, v1
	v_mov_b32_e32 v17, v0
	v_lshl_add_u64 v[4:5], v[4:5], 0, v[16:17]
	v_lshl_add_u64 v[2:3], s[14:15], 0, v[2:3]
	v_lshl_add_u64 v[2:3], v[2:3], 0, v[16:17]
	global_load_dwordx4 v[160:163], v[4:5], off
	global_load_dwordx4 v[164:167], v[2:3], off
	v_add_u32_e32 v19, 1, v210
	v_cvt_f32_u32_e32 v19, v19
	v_and_b32_e32 v20, 31, v18
	v_ashrrev_i32_e32 v21, 5, v18
	v_lshlrev_b32_e32 v22, 2, v18
	v_bfe_u32 v23, v18, 2, 2
	s_movk_i32 s16, 0x90
	v_mul_lo_u32 v25, v211, s16
	v_lshlrev_b32_e32 v27, 6, v21
	v_mul_u32_u24_e32 v20, 0x90, v20
	v_bitop3_b32 v212, v22, s66, v240 bitop3:0x6c
	v_lshl_or_b32 v22, v21, 2, v23
	v_lshlrev_b32_e32 v21, 4, v21
	s_mov_b32 s16, 0x42fc0000
	v_add3_u32 v216, 0, v20, v21
	v_cmp_lt_f32_e32 vcc, s16, v19
	v_mov_b32_e32 v20, 0x42800000
	v_and_b32_e32 v24, 16, v18
	v_cndmask_b32_e32 v20, 0, v20, vcc
	v_sub_f32_e32 v19, v20, v19
	v_exp_f32_e32 v19, v19
	v_lshlrev_b32_e32 v18, 3, v18
	v_mul_lo_u32 v22, v22, s70
	v_not_b32_e32 v20, 63
	v_lshlrev_b32_e32 v23, 1, v24
	v_and_b32_e32 v18, 24, v18
	v_add_u32_e32 v21, 0, v22
	v_cndmask_b32_e32 v20, 0, v20, vcc
	v_add3_u32 v218, v21, v23, v18
	v_ldexp_f32 v18, v19, v20
	v_mul_f32_e32 v186, 0x3fb8aa3b, v18
	s_lshl_b64 s[16:17], 1, s84
	v_mov_b32_e32 v14, v0
	v_mov_b32_e32 v15, v0
	v_mul_lo_u32 v26, v211, s70
	v_sub_u32_e32 v24, v27, v188
	v_mul_f32_e32 v190, 0x41800000, v186
	v_lshl_add_u64 v[194:195], s[14:15], 0, v[16:17]
	s_not_b64 s[14:15], s[16:17]
	v_mov_b32_e32 v1, v0
	v_mov_b32_e32 v2, v0
	v_mov_b32_e32 v3, v0
	v_mov_b32_e32 v4, v0
	v_mov_b32_e32 v5, v0
	v_mov_b32_e32 v6, v0
	v_mov_b32_e32 v7, v0
	v_mov_b32_e32 v8, v0
	v_mov_b32_e32 v9, v0
	v_mov_b32_e32 v10, v0
	v_mov_b32_e32 v11, v0
	v_mov_b32_e32 v12, v0
	v_mov_b32_e32 v13, v0
	v_add3_u32 v214, 0, v25, v16
	v_add3_u32 v215, 0, v26, v16
	v_add_u32_e32 v217, 31, v24
	v_lshl_add_u64 v[192:193], s[18:19], 0, v[16:17]
	v_add_f32_e32 v191, v190, v190
	s_andn2_b64 s[4:5], s[14:15], s[4:5]
	v_mov_b64_e32 v[30:31], v[14:15]
	v_mov_b64_e32 v[46:47], v[14:15]
	v_lshlrev_b32_e32 v183, 6, v210
	s_mov_b32 s88, 0
	v_mov_b32_e32 v219, 0xefa18f08
	v_mov_b32_e32 v213, 0
	v_mul_f32_e32 v189, 0.5, v186
	s_add_i32 s69, s69, -2
	v_fmamk_f32 v187, v186, 0x41800000, v191
	v_mov_b64_e32 v[28:29], v[12:13]
	v_mov_b64_e32 v[26:27], v[10:11]
	v_mov_b64_e32 v[24:25], v[8:9]
	v_mov_b64_e32 v[22:23], v[6:7]
	v_mov_b64_e32 v[20:21], v[4:5]
	v_mov_b64_e32 v[18:19], v[2:3]
	v_mov_b64_e32 v[16:17], v[0:1]
	v_mov_b64_e32 v[44:45], v[12:13]
	v_mov_b64_e32 v[42:43], v[10:11]
	v_mov_b64_e32 v[40:41], v[8:9]
	v_mov_b64_e32 v[38:39], v[6:7]
	v_mov_b64_e32 v[36:37], v[4:5]
	v_mov_b64_e32 v[34:35], v[2:3]
	v_mov_b64_e32 v[32:33], v[0:1]
	s_mov_b32 s90, s84
	s_mov_b64 s[14:15], s[4:5]
	s_mov_b64 s[22:23], s[14:15]
	s_mov_b32 s20, 0
	s_cmp_eq_u64 s[22:23], 0
	s_cbranch_scc1 .Lm0_pre_nob1
	s_flbit_i32_b64 s89, s[22:23]
	s_xor_b32 s89, s89, 63
	s_lshl_b64 s[16:17], 1, s89
	s_andn2_b64 s[22:23], s[22:23], s[16:17]
	v_lshl_add_u32 v2, s89, 6, v211
	v_ashrrev_i32_e32 v3, 31, v2
	v_lshlrev_b64 v[2:3], 8, v[2:3]
	v_lshl_add_u64 v[4:5], v[192:193], 0, v[2:3]
	v_lshl_add_u64 v[2:3], v[194:195], 0, v[2:3]
	global_load_dwordx4 v[226:229], v[4:5], off
	global_load_dwordx4 v[230:233], v[2:3], off
	s_mov_b32 s20, 1
	s_waitcnt vmcnt(2)
	s_branch .Lm0_pre_w

; #define LAS __attribute__((address_space(3)))
; template <int MODE  > ...
;     ...
;     {
;         LAS bf16_t* kb = (LAS bf16_t*)(lds + A_KBUF) + cur * 64 * KPITCH;
;         *(LAS u32x4*)(kb + skey * KPITCH + schunk * 8) = kreg;
;         if (NEEDV) { LAS bf16_t* vb = (LAS bf16_t*)(lds + A_VBUF) + cur * 64 * VPITCH;
;             *(LAS u32x4*)(vb + skey * VPITCH + schunk * 8) = vreg; }
;     }
;     __syncthreads();
;     for (;;) {
;         const bool has_next = rem != 0ull; int jn = 0;
;         if (has_next) { jn = 63 - __builtin_clzll(rem); rem &= ~(1ull << jn);
;             kreg = *(const u32x4*)(Kg + (size_t)(64 * jn + skey) * 128 + schunk * 8);
;             if (NEEDV) vreg = *(const u32x4*)(Vg + (size_t)(64 * jn + skey) * 128 + schunk * 8); }
.Lm0_pre_w:
	s_waitcnt lgkmcnt(0)
	ds_write_b128 v214, v[160:163]
	ds_write_b128 v215, v[164:167] offset:18432
	s_waitcnt lgkmcnt(0)
	s_barrier
.LBB0_146:
	s_mov_b32 s21, 0
	s_cmp_eq_u64 s[22:23], 0
	s_cbranch_scc1 .Lm0_noload
	s_flbit_i32_b64 s91, s[22:23]
	s_xor_b32 s91, s91, 63
	s_lshl_b64 vcc, 1, s91
	s_andn2_b64 s[22:23], s[22:23], vcc
	s_mov_b32 s21, 1
	v_lshl_add_u32 v2, s91, 6, v211
	v_ashrrev_i32_e32 v3, 31, v2
	v_lshlrev_b64 v[2:3], 8, v[2:3]
	v_lshl_add_u64 v[4:5], v[192:193], 0, v[2:3]
	v_lshl_add_u64 v[2:3], v[194:195], 0, v[2:3]
	s_cmp_eq_u32 s88, 0
	s_cbranch_scc0 .Lm0_loadB
	global_load_dwordx4 v[160:163], v[4:5], off
	global_load_dwordx4 v[164:167], v[2:3], off
	s_branch .Lm0_noload

; #define LAS __attribute__((address_space(3)))
; template <int MODE  > ...
;     ...
;             const LAS bf16_t* kb = (const LAS bf16_t*)(lds + A_KBUF) + cur * 64 * KPITCH;
;             constexpr int STEP = CMPM ? 16 : 1;
;             const int Bint = CMPM ? (1024 * j + 31 - t + 64 * h) : (64 * j - t + 4 * h);
;             const float sl = slope2 * (float)STEP;
;             const float mref = st.m; const bool fresh = !(mref > -1e28f);
;             const float mest = fresh ? 0.f : mref;
;             const float basef = selbit ? (slope2 * (float)Bint - mest) : -1e30f;
;             int ptype;
;             if (MODE == 1) ptype = (j == cblk) ? 1 : 0;
;             else if (MODE == 2) ptype = (j == cblk) ? 1 : ((j == cblk - 8) ? 2 : 0);
;             else ptype = (64 * j + 63 <= 4 * cblk - 2) ? 0 : 1;
;             f32x16 s0, s1;
;             { const float sl2 = sl + sl, sl3 = sl2 + sl;
; #pragma unroll
;               for (int g8 = 0; g8 < 4; ++g8) {
;                   const float b0 = __builtin_fmaf(sl, (float)(8 * g8), basef), b1 = __builtin_fmaf(sl, (float)(8 * g8 + 32), basef);
;                   s0[4 * g8] = b0; s0[4 * g8 + 1] = b0 + sl; s0[4 * g8 + 2] = b0 + sl2; s0[4 * g8 + 3] = b0 + sl3;
;                   s1[4 * g8] = b1; s1[4 * g8 + 1] = b1 + sl; s1[4 * g8 + 2] = b1 + sl2; s1[4 * g8 + 3] = b1 + sl3;
;               } }
;             if (ptype == 1) {
;                 const float thr = 0.5f * slope2 - mest;
; #pragma unroll
;                 for (int i = 0; i < 16; ++i) { s0[i] = (s0[i] < thr) ? s0[i] : -1e30f; s1[i] = (s1[i] < thr) ? s1[i] : -1e30f; }
;             } else if (ptype == 2) {
;                 const float thr = -511.5f * slope2 - mest;
; #pragma unroll
;                 for (int i = 0; i < 16; ++i) { s0[i] = (s0[i] > thr) ? s0[i] : -1e30f; s1[i] = (s1[i] > thr) ? s1[i] : -1e30f; }
;             }
.Lm0_noload:
.Lm0_body:
	s_mul_i32 vcc_lo, s88, 0x2400
	s_mul_i32 vcc_hi, s88, 0x3000
	v_add_u32_e32 v254, vcc_lo, v216
	v_add_u32_e32 v225, vcc_hi, v218
	ds_read_b128 v[80:83], v254
	ds_read_b128 v[84:87], v254 offset:4608
	ds_read_b128 v[88:91], v254 offset:32
	ds_read_b128 v[92:95], v254 offset:4640
	ds_read_b128 v[96:99], v254 offset:64
	ds_read_b128 v[100:103], v254 offset:4672
	ds_read_b128 v[104:107], v254 offset:96
	ds_read_b128 v[108:111], v254 offset:4704
	v_lshl_add_u32 v1, s90, 10, v217
	v_cvt_f32_i32_e32 v48, v1
	v_cmp_nlt_f32_e64 s[14:15], s71, v219
	s_lshl_b32 s17, s90, 6
	s_or_b32 s17, s17, 63
	s_cmp_le_i32 s17, s69
	v_cndmask_b32_e64 v1, v219, 0, s[14:15]
	v_fma_f32 v60, v186, v48, -v1
	v_fma_f32 v64, 0, v190, v60
	v_fmamk_f32 v68, v190, 0x41000000, v60
	v_fmamk_f32 v72, v190, 0x41800000, v60
	v_fmamk_f32 v76, v190, 0x41c00000, v60
	v_fmamk_f32 v48, v190, 0x42000000, v60
	v_fmamk_f32 v52, v190, 0x42200000, v60
	v_fmamk_f32 v56, v190, 0x42400000, v60
	v_fmac_f32_e32 v60, 0x42600000, v190
	v_add_f32_e32 v65, v190, v64
	v_add_f32_e32 v66, v191, v64
	v_add_f32_e32 v67, v187, v64
	v_add_f32_e32 v69, v190, v68
	v_add_f32_e32 v70, v191, v68
	v_add_f32_e32 v71, v187, v68
	v_add_f32_e32 v73, v190, v72
	v_add_f32_e32 v74, v191, v72
	v_add_f32_e32 v75, v187, v72
	v_add_f32_e32 v77, v190, v76
	v_add_f32_e32 v78, v191, v76
	v_add_f32_e32 v79, v187, v76
	v_add_f32_e32 v49, v190, v48
	v_add_f32_e32 v50, v191, v48
	v_add_f32_e32 v51, v187, v48
	v_add_f32_e32 v53, v190, v52
	v_add_f32_e32 v54, v191, v52
	v_add_f32_e32 v55, v187, v52
	v_add_f32_e32 v57, v190, v56
	v_add_f32_e32 v58, v191, v56
	v_add_f32_e32 v59, v187, v56
	v_add_f32_e32 v61, v190, v60
	v_add_f32_e32 v62, v191, v60
	v_add_f32_e32 v63, v187, v60
	s_cbranch_scc1 .Lm0_qk
	v_sub_f32_e32 v253, v189, v1
	v_cmp_lt_f32_e32 vcc, v64, v253
	s_nop 1
	v_cndmask_b32_e32 v64, v241, v64, vcc
	v_cmp_lt_f32_e32 vcc, v65, v253
	s_nop 1
	v_cndmask_b32_e32 v65, v241, v65, vcc
	v_cmp_lt_f32_e32 vcc, v66, v253
	s_nop 1
	v_cndmask_b32_e32 v66, v241, v66, vcc
	v_cmp_lt_f32_e32 vcc, v67, v253
	s_nop 1
	v_cndmask_b32_e32 v67, v241, v67, vcc
	v_cmp_lt_f32_e32 vcc, v68, v253
	s_nop 1
	v_cndmask_b32_e32 v68, v241, v68, vcc
	v_cmp_lt_f32_e32 vcc, v69, v253
	s_nop 1
	v_cndmask_b32_e32 v69, v241, v69, vcc
	v_cmp_lt_f32_e32 vcc, v70, v253
	s_nop 1
	v_cndmask_b32_e32 v70, v241, v70, vcc
	v_cmp_lt_f32_e32 vcc, v71, v253
	s_nop 1
	v_cndmask_b32_e32 v71, v241, v71, vcc
	v_cmp_lt_f32_e32 vcc, v72, v253
	s_nop 1
	v_cndmask_b32_e32 v72, v241, v72, vcc
	v_cmp_lt_f32_e32 vcc, v73, v253
	s_nop 1
	v_cndmask_b32_e32 v73, v241, v73, vcc
	v_cmp_lt_f32_e32 vcc, v74, v253
	s_nop 1
	v_cndmask_b32_e32 v74, v241, v74, vcc
	v_cmp_lt_f32_e32 vcc, v75, v253
	s_nop 1
	v_cndmask_b32_e32 v75, v241, v75, vcc
	v_cmp_lt_f32_e32 vcc, v76, v253
	s_nop 1
	v_cndmask_b32_e32 v76, v241, v76, vcc
	v_cmp_lt_f32_e32 vcc, v77, v253
	s_nop 1
	v_cndmask_b32_e32 v77, v241, v77, vcc
	v_cmp_lt_f32_e32 vcc, v78, v253
	s_nop 1
	v_cndmask_b32_e32 v78, v241, v78, vcc
	v_cmp_lt_f32_e32 vcc, v79, v253
	s_nop 1
	v_cndmask_b32_e32 v79, v241, v79, vcc
	v_cmp_lt_f32_e32 vcc, v48, v253
	s_nop 1
	v_cndmask_b32_e32 v48, v241, v48, vcc
	v_cmp_lt_f32_e32 vcc, v49, v253
	s_nop 1
	v_cndmask_b32_e32 v49, v241, v49, vcc
	v_cmp_lt_f32_e32 vcc, v50, v253
	s_nop 1
	v_cndmask_b32_e32 v50, v241, v50, vcc
	v_cmp_lt_f32_e32 vcc, v51, v253
	s_nop 1
	v_cndmask_b32_e32 v51, v241, v51, vcc
	v_cmp_lt_f32_e32 vcc, v52, v253
	s_nop 1
	v_cndmask_b32_e32 v52, v241, v52, vcc
	v_cmp_lt_f32_e32 vcc, v53, v253
	s_nop 1
	v_cndmask_b32_e32 v53, v241, v53, vcc
	v_cmp_lt_f32_e32 vcc, v54, v253
	s_nop 1
	v_cndmask_b32_e32 v54, v241, v54, vcc
	v_cmp_lt_f32_e32 vcc, v55, v253
	s_nop 1
	v_cndmask_b32_e32 v55, v241, v55, vcc
	v_cmp_lt_f32_e32 vcc, v56, v253
	s_nop 1
	v_cndmask_b32_e32 v56, v241, v56, vcc
	v_cmp_lt_f32_e32 vcc, v57, v253
	s_nop 1
	v_cndmask_b32_e32 v57, v241, v57, vcc
	v_cmp_lt_f32_e32 vcc, v58, v253
	s_nop 1
	v_cndmask_b32_e32 v58, v241, v58, vcc
	v_cmp_lt_f32_e32 vcc, v59, v253
	s_nop 1
	v_cndmask_b32_e32 v59, v241, v59, vcc
	v_cmp_lt_f32_e32 vcc, v60, v253
	s_nop 1
	v_cndmask_b32_e32 v60, v241, v60, vcc
	v_cmp_lt_f32_e32 vcc, v61, v253
	s_nop 1
	v_cndmask_b32_e32 v61, v241, v61, vcc
	v_cmp_lt_f32_e32 vcc, v62, v253
	s_nop 1
	v_cndmask_b32_e32 v62, v241, v62, vcc
	v_cmp_lt_f32_e32 vcc, v63, v253
	s_nop 1
	v_cndmask_b32_e32 v63, v241, v63, vcc
; template <int MODE  > ...
;     ...
;             for (int kk = 0; kk < 4; ++kk) {
;                 const bf16x8 k0 = *(const LAS bf16x8*)(kb + col * KPITCH + kk * 16 + h * 8);
;                 const bf16x8 k1 = *(const LAS bf16x8*)(kb + (32 + col) * KPITCH + kk * 16 + h * 8);
;                 s0 = __builtin_amdgcn_mfma_f32_32x32x16_bf16(k0, qf[kk], s0, 0, 0, 0);
;                 s1 = __builtin_amdgcn_mfma_f32_32x32x16_bf16(k1, qf[kk], s1, 0, 0, 0);
;             }
;             if (MODE != 3) {
;                 float mx = fmaxf(s0[0], s1[0]);
; #pragma unroll
;                 for (int i = 1; i < 16; ++i) mx = fmaxf(mx, fmaxf(s0[i], s1[i]));
;                 mx = fmaxf(mx, shflx(mx, 32, lane));
;                 float alpha = 1.f;
;                 if (__builtin_amdgcn_ballot_w64(fresh || mx > 0.f) != 0ull) {
;                     const float moldr = fresh ? -1e29f : 0.f, mnewr = fmaxf(moldr, mx);
;                     alpha = __builtin_amdgcn_exp2f(moldr - mnewr);
;                     st.m = mest + mnewr;
; #pragma unroll
;                     for (int i = 0; i < 16; ++i) { s0[i] = __builtin_amdgcn_exp2f(s0[i] - mnewr); s1[i] = __builtin_amdgcn_exp2f(s1[i] - mnewr); }
;                     st.o0 *= alpha; st.o1 *= alpha;
;                 } else {
; #pragma unroll
;                     for (int i = 0; i < 16; ++i) { s0[i] = __builtin_amdgcn_exp2f(s0[i]); s1[i] = __builtin_amdgcn_exp2f(s1[i]); }
;                 }
;                 { typedef float f32x8 __attribute__((ext_vector_type(8)));
;                   const f32x16 t16 = s0 + s1;
;                   const f32x8 t8 = __builtin_shufflevector(t16, t16, 0, 1, 2, 3, 4, 5, 6, 7) + __builtin_shufflevector(t16, t16, 8, 9, 10, 11, 12, 13, 14, 15);
;                   const f32x4 t4 = __builtin_shufflevector(t8, t8, 0, 1, 2, 3) + __builtin_shufflevector(t8, t8, 4, 5, 6, 7);
;                   float ps = (t4[0] + t4[1]) + (t4[2] + t4[3]);
;                   ps += shflx(ps, 32, lane);
;                   st.l = st.l * alpha + ps; }
;                 bf16x8 pf[4];
; #pragma unroll
;                 for (int kk = 0; kk < 4; ++kk) {
;                     u32x4 pw;
;                     if (kk < 2) { pw.x = pk2(s0[8 * kk], s0[8 * kk + 1]); pw.y = pk2(s0[8 * kk + 2], s0[8 * kk + 3]); pw.z = pk2(s0[8 * kk + 4], s0[8 * kk + 5]); pw.w = pk2(s0[8 * kk + 6], s0[8 * kk + 7]); }
.Lm0_qk:
	s_waitcnt lgkmcnt(7)
	v_mfma_f32_32x32x16_bf16 v[64:79], v[80:83], v[144:147], v[64:79]
	s_waitcnt lgkmcnt(6)
	v_mfma_f32_32x32x16_bf16 v[48:63], v[84:87], v[144:147], v[48:63]
	s_waitcnt lgkmcnt(5)
	v_mfma_f32_32x32x16_bf16 v[64:79], v[88:91], v[148:151], v[64:79]
	s_waitcnt lgkmcnt(4)
	v_mfma_f32_32x32x16_bf16 v[48:63], v[92:95], v[148:151], v[48:63]
	s_waitcnt lgkmcnt(3)
	v_mfma_f32_32x32x16_bf16 v[64:79], v[96:99], v[152:155], v[64:79]
	s_waitcnt lgkmcnt(2)
	v_mfma_f32_32x32x16_bf16 v[48:63], v[100:103], v[152:155], v[48:63]
	s_waitcnt lgkmcnt(1)
	v_mfma_f32_32x32x16_bf16 v[64:79], v[104:107], v[156:159], v[64:79]
	s_waitcnt lgkmcnt(0)
	v_mfma_f32_32x32x16_bf16 v[48:63], v[108:111], v[156:159], v[48:63]
	ds_read_b64_tr_b16 v[80:81], v225 offset:18432
	ds_read_b64_tr_b16 v[82:83], v225 offset:19968
	ds_read_b64_tr_b16 v[84:85], v225 offset:18496
	ds_read_b64_tr_b16 v[86:87], v225 offset:20032
	ds_read_b64_tr_b16 v[88:89], v225 offset:21504
	ds_read_b64_tr_b16 v[90:91], v225 offset:23040
	ds_read_b64_tr_b16 v[92:93], v225 offset:21568
	ds_read_b64_tr_b16 v[94:95], v225 offset:23104
	s_nop 3
	v_max3_f32 v234, v64, v65, v66
	v_max3_f32 v234, v234, v67, v68
	v_max3_f32 v234, v234, v69, v70
	v_max3_f32 v234, v234, v71, v72
	v_max3_f32 v234, v234, v73, v74
	v_max3_f32 v234, v234, v75, v76
	v_max3_f32 v234, v234, v77, v78
	v_max3_f32 v235, v48, v49, v50
	v_max3_f32 v235, v235, v51, v52
	v_max3_f32 v235, v235, v53, v54
	v_max3_f32 v235, v235, v55, v56
	v_max3_f32 v235, v235, v57, v58
	v_max3_f32 v235, v235, v59, v60
	v_max3_f32 v235, v235, v61, v62
	v_max3_f32 v234, v234, v79, v63
	v_max_f32_e32 v234, v234, v235
	v_mov_b32_e32 v235, v234
	s_waitcnt lgkmcnt(7)
	ds_read_b64_tr_b16 v[96:97], v225 offset:24576
	ds_read_b64_tr_b16 v[98:99], v225 offset:26112
	ds_read_b64_tr_b16 v[100:101], v225 offset:24640
	ds_read_b64_tr_b16 v[102:103], v225 offset:26176
	ds_read_b64_tr_b16 v[104:105], v225 offset:27648
	ds_read_b64_tr_b16 v[106:107], v225 offset:29184
	ds_read_b64_tr_b16 v[108:109], v225 offset:27712
	ds_read_b64_tr_b16 v[110:111], v225 offset:29248
	v_permlane32_swap_b32_e32 v235, v234
	v_max_f32_e32 v234, v234, v235
	v_cmp_lt_f32_e32 vcc, 0, v234
	s_or_b64 vcc, s[14:15], vcc
	s_cbranch_vccz .Lm0_norescale
	v_cndmask_b32_e64 v235, 0, v242, s[14:15]
	v_max_f32_e32 v234, v235, v234
	v_sub_f32_e32 v235, v235, v234
	v_exp_f32_e32 v6, v235
	v_add_f32_e32 v219, v1, v234
	v_sub_f32_e32 v128, v64, v234
	v_exp_f32_e32 v128, v128
	v_sub_f32_e32 v112, v48, v234
	v_exp_f32_e32 v112, v112
	v_sub_f32_e32 v129, v65, v234
	v_exp_f32_e32 v129, v129
	v_sub_f32_e32 v113, v49, v234
	v_exp_f32_e32 v113, v113
	v_sub_f32_e32 v130, v66, v234
	v_exp_f32_e32 v130, v130
	v_sub_f32_e32 v114, v50, v234
	v_exp_f32_e32 v114, v114
	v_sub_f32_e32 v131, v67, v234
	v_exp_f32_e32 v131, v131
	v_sub_f32_e32 v115, v51, v234
	v_exp_f32_e32 v115, v115
	v_sub_f32_e32 v132, v68, v234
	v_exp_f32_e32 v132, v132
	v_sub_f32_e32 v116, v52, v234
	v_exp_f32_e32 v116, v116
	v_sub_f32_e32 v133, v69, v234
	v_exp_f32_e32 v133, v133
	v_sub_f32_e32 v117, v53, v234
	v_exp_f32_e32 v117, v117
	v_sub_f32_e32 v134, v70, v234
	v_exp_f32_e32 v134, v134
	v_sub_f32_e32 v118, v54, v234
	v_exp_f32_e32 v118, v118
	v_sub_f32_e32 v135, v71, v234
	v_exp_f32_e32 v135, v135
	v_sub_f32_e32 v119, v55, v234
	v_exp_f32_e32 v119, v119
	v_sub_f32_e32 v136, v72, v234
	v_exp_f32_e32 v136, v136
	v_sub_f32_e32 v120, v56, v234
	v_exp_f32_e32 v120, v120
	v_sub_f32_e32 v137, v73, v234
	v_exp_f32_e32 v137, v137
	v_sub_f32_e32 v121, v57, v234
	v_exp_f32_e32 v121, v121
	v_sub_f32_e32 v138, v74, v234
	v_exp_f32_e32 v138, v138
	v_sub_f32_e32 v122, v58, v234
	v_exp_f32_e32 v122, v122
	v_sub_f32_e32 v139, v75, v234
	v_exp_f32_e32 v139, v139
	v_sub_f32_e32 v123, v59, v234
	v_exp_f32_e32 v123, v123
	v_sub_f32_e32 v140, v76, v234
	v_exp_f32_e32 v140, v140
	v_sub_f32_e32 v124, v60, v234
	v_exp_f32_e32 v124, v124
	v_sub_f32_e32 v141, v77, v234
	v_exp_f32_e32 v141, v141
	v_sub_f32_e32 v125, v61, v234
	v_exp_f32_e32 v125, v125
	v_sub_f32_e32 v142, v78, v234
	v_exp_f32_e32 v142, v142
	v_sub_f32_e32 v126, v62, v234
	v_exp_f32_e32 v126, v126
	v_sub_f32_e32 v143, v79, v234
	v_exp_f32_e32 v143, v143
	v_sub_f32_e32 v127, v63, v234
	v_exp_f32_e32 v127, v127
	v_pk_mul_f32 v[16:17], v[16:17], v[6:7] op_sel_hi:[1,0]
	v_pk_mul_f32 v[18:19], v[18:19], v[6:7] op_sel_hi:[1,0]
	v_pk_mul_f32 v[20:21], v[20:21], v[6:7] op_sel_hi:[1,0]
	v_pk_mul_f32 v[22:23], v[22:23], v[6:7] op_sel_hi:[1,0]
	v_pk_mul_f32 v[24:25], v[24:25], v[6:7] op_sel_hi:[1,0]
	v_pk_mul_f32 v[26:27], v[26:27], v[6:7] op_sel_hi:[1,0]
	v_pk_mul_f32 v[28:29], v[28:29], v[6:7] op_sel_hi:[1,0]
	v_pk_mul_f32 v[30:31], v[30:31], v[6:7] op_sel_hi:[1,0]
	v_pk_mul_f32 v[32:33], v[32:33], v[6:7] op_sel_hi:[1,0]
	v_pk_mul_f32 v[34:35], v[34:35], v[6:7] op_sel_hi:[1,0]
	v_pk_mul_f32 v[36:37], v[36:37], v[6:7] op_sel_hi:[1,0]
	v_pk_mul_f32 v[38:39], v[38:39], v[6:7] op_sel_hi:[1,0]
	v_pk_mul_f32 v[40:41], v[40:41], v[6:7] op_sel_hi:[1,0]
	v_pk_mul_f32 v[42:43], v[42:43], v[6:7] op_sel_hi:[1,0]
	v_pk_mul_f32 v[44:45], v[44:45], v[6:7] op_sel_hi:[1,0]
	v_pk_mul_f32 v[46:47], v[46:47], v[6:7] op_sel_hi:[1,0]
	s_branch .Lm0_pv
; #define LAS __attribute__((address_space(3)))
; template <int MODE  > ...
;     ...
;                 } else {
; #pragma unroll
;                     for (int i = 0; i < 16; ++i) { s0[i] = __builtin_amdgcn_exp2f(s0[i]); s1[i] = __builtin_amdgcn_exp2f(s1[i]); }
;                 }
;                 { typedef float f32x8 __attribute__((ext_vector_type(8)));
;                   const f32x16 t16 = s0 + s1;
;                   const f32x8 t8 = __builtin_shufflevector(t16, t16, 0, 1, 2, 3, 4, 5, 6, 7) + __builtin_shufflevector(t16, t16, 8, 9, 10, 11, 12, 13, 14, 15);
;                   const f32x4 t4 = __builtin_shufflevector(t8, t8, 0, 1, 2, 3) + __builtin_shufflevector(t8, t8, 4, 5, 6, 7);
;                   float ps = (t4[0] + t4[1]) + (t4[2] + t4[3]);
;                   ps += shflx(ps, 32, lane);
;                   st.l = st.l * alpha + ps; }
;                 bf16x8 pf[4];
; #pragma unroll
;                 for (int kk = 0; kk < 4; ++kk) {
;                     u32x4 pw;
;                     if (kk < 2) { pw.x = pk2(s0[8 * kk], s0[8 * kk + 1]); pw.y = pk2(s0[8 * kk + 2], s0[8 * kk + 3]); pw.z = pk2(s0[8 * kk + 4], s0[8 * kk + 5]); pw.w = pk2(s0[8 * kk + 6], s0[8 * kk + 7]); }
;                     else { const int k2 = kk - 2; pw.x = pk2(s1[8 * k2], s1[8 * k2 + 1]); pw.y = pk2(s1[8 * k2 + 2], s1[8 * k2 + 3]); pw.z = pk2(s1[8 * k2 + 4], s1[8 * k2 + 5]); pw.w = pk2(s1[8 * k2 + 6], s1[8 * k2 + 7]); }
;                     pf[kk] = __builtin_bit_cast(bf16x8, pw);
;                 }
;                 const LAS bf16_t* vb = (const LAS bf16_t*)(lds + A_VBUF) + cur * 64 * VPITCH + (4 * h + ((lane & 15) >> 2)) * VPITCH + ((lane >> 4) & 1) * 16 + 4 * (lane & 3);
; #pragma unroll
;                 for (int kk = 0; kk < 4; ++kk) {
;                     typedef short v4i16_t __attribute__((ext_vector_type(4)));
;                     const v4i16_t a0 = __builtin_amdgcn_ds_read_tr16_b64_v4i16((LAS v4i16_t*)(vb + (16 * kk) * VPITCH));
;                     const v4i16_t a1 = __builtin_amdgcn_ds_read_tr16_b64_v4i16((LAS v4i16_t*)(vb + (16 * kk + 8) * VPITCH));
;                     const v4i16_t b0 = __builtin_amdgcn_ds_read_tr16_b64_v4i16((LAS v4i16_t*)(vb + (16 * kk) * VPITCH + 32));
;                     const v4i16_t b1 = __builtin_amdgcn_ds_read_tr16_b64_v4i16((LAS v4i16_t*)(vb + (16 * kk + 8) * VPITCH + 32));
.Lm0_norescale:
	v_exp_f32_e32 v128, v64
	v_exp_f32_e32 v112, v48
	v_exp_f32_e32 v129, v65
	v_exp_f32_e32 v113, v49
	v_exp_f32_e32 v130, v66
	v_exp_f32_e32 v114, v50
	v_exp_f32_e32 v131, v67
	v_exp_f32_e32 v115, v51
	v_exp_f32_e32 v132, v68
	v_exp_f32_e32 v116, v52
	v_exp_f32_e32 v133, v69
	v_exp_f32_e32 v117, v53
	v_exp_f32_e32 v134, v70
	v_exp_f32_e32 v118, v54
	v_exp_f32_e32 v135, v71
	v_exp_f32_e32 v119, v55
	v_exp_f32_e32 v136, v72
	v_exp_f32_e32 v120, v56
	v_exp_f32_e32 v137, v73
	v_exp_f32_e32 v121, v57
	v_exp_f32_e32 v138, v74
	v_exp_f32_e32 v122, v58
	v_exp_f32_e32 v139, v75
	v_exp_f32_e32 v123, v59
	v_exp_f32_e32 v140, v76
	v_exp_f32_e32 v124, v60
	v_exp_f32_e32 v141, v77
	v_exp_f32_e32 v125, v61
	v_exp_f32_e32 v142, v78
	v_exp_f32_e32 v126, v62
	v_exp_f32_e32 v143, v79
	v_exp_f32_e32 v127, v63
	v_mov_b32_e32 v6, 1.0
.Lm0_pv:
	v_cvt_pk_bf16_f32 v64, v128, v129
	v_cvt_pk_bf16_f32 v65, v130, v131
	v_cvt_pk_bf16_f32 v66, v132, v133
	v_cvt_pk_bf16_f32 v67, v134, v135
	s_waitcnt lgkmcnt(0)
	s_nop 0
	v_mfma_f32_32x32x16_bf16 v[16:31], v[80:83], v[64:67], v[16:31]
	v_mfma_f32_32x32x16_bf16 v[32:47], v[84:87], v[64:67], v[32:47]
	v_cvt_pk_bf16_f32 v68, v136, v137
	v_cvt_pk_bf16_f32 v69, v138, v139
	v_cvt_pk_bf16_f32 v70, v140, v141
	v_cvt_pk_bf16_f32 v71, v142, v143
	v_pk_add_f32 v[62:63], v[112:113], v[128:129]
	v_pk_add_f32 v[60:61], v[116:117], v[132:133]
	v_pk_add_f32 v[48:49], v[120:121], v[136:137]
	v_pk_add_f32 v[58:59], v[124:125], v[140:141]
	v_pk_add_f32 v[56:57], v[118:119], v[134:135]
	v_mfma_f32_32x32x16_bf16 v[16:31], v[88:91], v[68:71], v[16:31]
	v_mfma_f32_32x32x16_bf16 v[32:47], v[92:95], v[68:71], v[32:47]
	v_cvt_pk_bf16_f32 v72, v112, v113
	v_cvt_pk_bf16_f32 v73, v114, v115
	v_cvt_pk_bf16_f32 v74, v116, v117
	v_cvt_pk_bf16_f32 v75, v118, v119
	v_pk_add_f32 v[54:55], v[126:127], v[142:143]
	v_pk_add_f32 v[50:51], v[122:123], v[138:139]
	v_pk_add_f32 v[52:53], v[114:115], v[130:131]
	v_pk_add_f32 v[58:59], v[60:61], v[58:59]
	v_pk_add_f32 v[48:49], v[62:63], v[48:49]
	v_mfma_f32_32x32x16_bf16 v[16:31], v[96:99], v[72:75], v[16:31]
	v_mfma_f32_32x32x16_bf16 v[32:47], v[100:103], v[72:75], v[32:47]
	v_cvt_pk_bf16_f32 v76, v120, v121
	v_cvt_pk_bf16_f32 v77, v122, v123
	v_cvt_pk_bf16_f32 v78, v124, v125
	v_cvt_pk_bf16_f32 v79, v126, v127
	v_pk_add_f32 v[54:55], v[56:57], v[54:55]
	v_pk_add_f32 v[50:51], v[52:53], v[50:51]
	v_pk_add_f32 v[48:49], v[48:49], v[58:59]
	v_pk_add_f32 v[50:51], v[50:51], v[54:55]
	v_mfma_f32_32x32x16_bf16 v[16:31], v[104:107], v[76:79], v[16:31]
	v_mfma_f32_32x32x16_bf16 v[32:47], v[108:111], v[76:79], v[32:47]
	v_add_f32_e32 v48, v48, v49
	v_add_f32_e32 v49, v50, v51
	v_add_f32_e32 v48, v48, v49
	v_mov_b32_e32 v49, v48
	s_nop 1
	v_permlane32_swap_b32_e32 v49, v48
	v_add_f32_e32 v48, v48, v49
	v_fmac_f32_e32 v48, v213, v6
	v_mov_b32_e32 v213, v48
.Lm0_stage:
	s_cmp_eq_u32 s20, 0
	s_cbranch_scc1 .Lm0_bot
	s_lshl_b32 s14, s88, 6
	s_xor_b32 s14, s14, 64
	s_mul_i32 s15, s14, 0x90
	v_add_u32_e32 v2, s15, v214
	s_mulk_i32 s14, 0xc0
	v_add_u32_e32 v3, s14, v215
	s_cmp_eq_u32 s21, 0
	s_cbranch_scc1 .Lm0_w0
	s_waitcnt vmcnt(2)
	s_branch .Lm0_w1

; #define LAS __attribute__((address_space(3)))
; template <int MODE  > ...
;     ...
;         if (has_next) {
;             LAS bf16_t* kb = (LAS bf16_t*)(lds + A_KBUF) + (cur ^ 1) * 64 * KPITCH;
;             *(LAS u32x4*)(kb + skey * KPITCH + schunk * 8) = kreg;
;             if (NEEDV) { LAS bf16_t* vb = (LAS bf16_t*)(lds + A_VBUF) + (cur ^ 1) * 64 * VPITCH;
;                 *(LAS u32x4*)(vb + skey * VPITCH + schunk * 8) = vreg; }
;         }
;         __syncthreads();
;         if (!has_next) break;
;         j = jn; cur ^= 1;
;     }
.Lm0_w1:
	s_cmp_eq_u32 s88, 0
	s_cbranch_scc0 .Lm0_stA
	ds_write_b128 v2, v[226:229]
	ds_write_b128 v3, v[230:233] offset:18432
	s_branch .Lm0_bot
.Lm0_stA:
	ds_write_b128 v2, v[160:163]
	ds_write_b128 v3, v[164:167] offset:18432
.Lm0_bot:
	s_xor_b32 s88, s88, 1
	s_waitcnt lgkmcnt(0)
	s_barrier
	s_cmp_eq_u32 s20, 0
	s_cbranch_scc1 .Lm0_exit
	s_mov_b32 s90, s89
	s_mov_b32 s89, s91
	s_mov_b32 s20, s21
	s_branch .LBB0_146
.Lm0_exit:
	s_nop 11
	v_mov_b32_e32 v1, v219
	v_mov_b32_e32 v3, v213

; __device__ __forceinline__ void attn_phase(unsigned char* ws, LAS unsigned char* lds, const int tid, const int bid, const int l) {
;     ...
;     while (u < 1024) {
;         __syncthreads();
;         if (tid == 0) slot[0] = (int)__hip_atomic_fetch_add(ctr, 1u, __ATOMIC_RELAXED, __HIP_MEMORY_SCOPE_AGENT);
;         int b, g, c;
;         if (u < 384) { g = 1; c = 63 - (u >> 3); b = u & 7; }
;         else if (u < 768) { const int v = u - 384; g = 0; c = 63 - (v >> 3); b = v & 7; }
;         else { const int v = u - 768; c = 15 - (v >> 4); g = (v >> 3) & 1; b = v & 7; }
;         attn_unit(ws, lds, b, g, c, tid);
;         __syncthreads();
;         u = slot[0];
;     }
; }
.LBB0_287:
	s_setprio 0
	s_mov_b64 s[4:5], 0
